# GEMM K-loops: fragment ds_reads issued right after the barrier, ahead of the next-tile address math and global loads
# baseline (speedup 1.0000x reference)
.LBB0_336:
	s_cmp_gt_u32 s90, 13
	s_cselect_b64 s[36:37], -1, 0
	s_and_b64 vcc, exec, s[36:37]
	s_waitcnt vmcnt(15)
	ds_write_b128 v131, v[2:5]
	s_waitcnt vmcnt(11)
	ds_write_b128 v131, v[14:17] offset:16384
	ds_write_b128 v131, v[10:13] offset:4096
	s_waitcnt vmcnt(10)
	ds_write_b128 v131, v[30:33] offset:20480
	ds_write_b128 v131, v[22:25] offset:8192
	s_waitcnt vmcnt(9)
	ds_write_b128 v131, v[46:49] offset:24576
	ds_write_b128 v131, v[38:41] offset:12288
	s_waitcnt vmcnt(8)
	ds_write_b128 v131, v[58:61] offset:28672
	s_waitcnt lgkmcnt(0)
	s_barrier
	ds_read_b128 v[138:141], v134
	ds_read_b128 v[142:145], v134 offset:2048
	ds_read_b128 v[146:149], v134 offset:4096
	ds_read_b128 v[150:153], v134 offset:6144
	ds_read_b128 v[154:157], v135 offset:16384
	ds_read_b128 v[158:161], v135 offset:18432
	ds_read_b128 v[162:165], v135 offset:20480
	ds_read_b128 v[166:169], v135 offset:22528
	s_cbranch_vccz .LBB0_338
	s_mov_b64 s[38:39], 0
	s_mov_b64 s[80:81], s[28:29]
	s_branch .LBB0_339

.LBB0_343:
	s_setprio 1
	s_waitcnt lgkmcnt(3)
	v_mfma_f32_16x16x32_bf16 v[126:129], v[138:141], v[154:157], v[126:129]
	s_waitcnt lgkmcnt(2)
	v_mfma_f32_16x16x32_bf16 v[122:125], v[138:141], v[158:161], v[122:125]
	s_waitcnt lgkmcnt(1)
	v_mfma_f32_16x16x32_bf16 v[114:117], v[138:141], v[162:165], v[114:117]
	s_waitcnt lgkmcnt(0)
	v_mfma_f32_16x16x32_bf16 v[106:109], v[138:141], v[166:169], v[106:109]
	v_mfma_f32_16x16x32_bf16 v[118:121], v[142:145], v[154:157], v[118:121]
	v_mfma_f32_16x16x32_bf16 v[110:113], v[142:145], v[158:161], v[110:113]
	v_mfma_f32_16x16x32_bf16 v[102:105], v[142:145], v[162:165], v[102:105]
	v_mfma_f32_16x16x32_bf16 v[98:101], v[142:145], v[166:169], v[98:101]
	v_mfma_f32_16x16x32_bf16 v[138:141], v[146:149], v[154:157], v[94:97]
	v_mfma_f32_16x16x32_bf16 v[142:145], v[146:149], v[158:161], v[90:93]
	v_mfma_f32_16x16x32_bf16 v[190:193], v[146:149], v[162:165], v[82:85]
	v_mfma_f32_16x16x32_bf16 v[146:149], v[146:149], v[166:169], v[74:77]
	v_mfma_f32_16x16x32_bf16 v[154:157], v[150:153], v[154:157], v[86:89]
	v_mfma_f32_16x16x32_bf16 v[158:161], v[150:153], v[158:161], v[78:81]
	v_mfma_f32_16x16x32_bf16 v[162:165], v[150:153], v[162:165], v[70:73]
	v_mfma_f32_16x16x32_bf16 v[150:153], v[150:153], v[166:169], v[66:69]
	s_setprio 0
	ds_read_b128 v[78:81], v136
	ds_read_b128 v[94:97], v136 offset:2048
	ds_read_b128 v[166:169], v136 offset:4096
	ds_read_b128 v[194:197], v136 offset:6144
	ds_read_b128 v[198:201], v137 offset:16384
	ds_read_b128 v[202:205], v137 offset:18432
	ds_read_b128 v[206:209], v137 offset:20480
	ds_read_b128 v[210:213], v137 offset:22528
	s_setprio 1
	s_waitcnt lgkmcnt(3)
	v_mfma_f32_16x16x32_bf16 v[66:69], v[78:81], v[198:201], v[126:129]
	s_waitcnt lgkmcnt(2)
	v_mfma_f32_16x16x32_bf16 v[70:73], v[78:81], v[202:205], v[122:125]
	s_waitcnt lgkmcnt(1)
	v_mfma_f32_16x16x32_bf16 v[74:77], v[78:81], v[206:209], v[114:117]
	s_waitcnt lgkmcnt(0)
	v_mfma_f32_16x16x32_bf16 v[78:81], v[78:81], v[210:213], v[106:109]
	v_mfma_f32_16x16x32_bf16 v[82:85], v[94:97], v[198:201], v[118:121]
	v_mfma_f32_16x16x32_bf16 v[86:89], v[94:97], v[202:205], v[110:113]
	v_mfma_f32_16x16x32_bf16 v[90:93], v[94:97], v[206:209], v[102:105]
	v_mfma_f32_16x16x32_bf16 v[94:97], v[94:97], v[210:213], v[98:101]
	v_mfma_f32_16x16x32_bf16 v[98:101], v[166:169], v[198:201], v[138:141]
	v_mfma_f32_16x16x32_bf16 v[102:105], v[166:169], v[202:205], v[142:145]
	v_mfma_f32_16x16x32_bf16 v[106:109], v[166:169], v[206:209], v[190:193]
	v_mfma_f32_16x16x32_bf16 v[110:113], v[166:169], v[210:213], v[146:149]
	v_mfma_f32_16x16x32_bf16 v[114:117], v[194:197], v[198:201], v[154:157]
	v_mfma_f32_16x16x32_bf16 v[118:121], v[194:197], v[202:205], v[158:161]
	v_mfma_f32_16x16x32_bf16 v[122:125], v[194:197], v[206:209], v[162:165]
	v_mfma_f32_16x16x32_bf16 v[126:129], v[194:197], v[210:213], v[150:153]
	s_setprio 0
	s_cmp_lt_u32 s90, 13
	s_cselect_b64 s[38:39], -1, 0
	s_or_b64 s[80:81], s[28:29], s[38:39]
	s_andn2_b64 vcc, exec, s[80:81]
	s_cbranch_vccnz .Lgin_sh_tail
	s_waitcnt vmcnt(15)
	ds_write_b128 v131, v[6:9] offset:32768
	s_waitcnt vmcnt(11)
	ds_write_b128 v131, v[18:21] offset:49152
	ds_write_b128 v131, v[26:29] offset:36864
	s_waitcnt vmcnt(10)
	ds_write_b128 v131, v[42:45] offset:53248
	ds_write_b128 v131, v[34:37] offset:40960
	s_waitcnt vmcnt(9)
	ds_write_b128 v131, v[54:57] offset:57344
	ds_write_b128 v131, v[50:53] offset:45056
	s_waitcnt vmcnt(8)
	ds_write_b128 v131, v[62:65] offset:61440
	s_branch .Lgin_sh_join

.Lgin_sh_join:
	s_waitcnt lgkmcnt(0)
	s_barrier
	ds_read_b128 v[138:141], v134 offset:32768
	ds_read_b128 v[142:145], v134 offset:34816
	ds_read_b128 v[146:149], v134 offset:36864
	ds_read_b128 v[150:153], v134 offset:38912
	ds_read_b128 v[154:157], v135 offset:49152
	ds_read_b128 v[158:161], v135 offset:51200
	ds_read_b128 v[162:165], v135 offset:53248
	ds_read_b128 v[166:169], v135 offset:55296
	s_cbranch_vccnz .LBB0_345
	s_and_b64 s[38:39], s[38:39], exec
	s_cselect_b32 s39, s25, s31
	s_cselect_b32 s38, s24, s30
	v_lshl_add_u64 v[6:7], s[38:39], 0, v[132:133]
	s_cselect_b32 s39, s27, s35
	s_cselect_b32 s38, s26, s34
	v_lshl_add_u64 v[8:9], s[38:39], 0, v[132:133]
	s_cselect_b32 s38, s77, 0xfffffcc0
	s_add_i32 s38, s38, s11
	s_add_i32 s42, s38, 0x380
	v_lshl_add_u64 v[8:9], v[8:9], 0, v[0:1]
	s_lshl_b64 s[38:39], s[42:43], 1
	v_lshl_add_u64 v[18:19], v[8:9], 0, s[38:39]
	v_add_co_u32_e32 v20, vcc, s33, v18
	v_lshl_add_u64 v[6:7], v[6:7], 0, v[0:1]
	s_nop 0
	v_addc_co_u32_e32 v21, vcc, 0, v19, vcc
	v_add_co_u32_e32 v34, vcc, 0x20000, v18
	v_lshl_add_u64 v[62:63], v[6:7], 0, s[38:39]
	s_nop 0
	v_addc_co_u32_e32 v35, vcc, 0, v19, vcc
	global_load_dwordx4 v[6:9], v[18:19], off
	v_add_co_u32_e32 v18, vcc, 0x30000, v18
	global_load_dwordx4 v[26:29], v[20:21], off
	s_nop 0
	global_load_dwordx4 v[34:37], v[34:35], off
	v_addc_co_u32_e32 v19, vcc, 0, v19, vcc
	v_add_co_u32_e32 v42, vcc, 0x10000, v62
	global_load_dwordx4 v[50:53], v[18:19], off
	s_nop 0
	global_load_dwordx4 v[18:21], v[62:63], off
	v_addc_co_u32_e32 v43, vcc, 0, v63, vcc
	v_add_co_u32_e32 v54, vcc, 0x20000, v62
	s_nop 1
	v_addc_co_u32_e32 v55, vcc, 0, v63, vcc
	v_add_co_u32_e32 v62, vcc, 0x30000, v62
	global_load_dwordx4 v[42:45], v[42:43], off
	s_nop 0
	global_load_dwordx4 v[54:57], v[54:55], off
	v_addc_co_u32_e32 v63, vcc, 0, v63, vcc
	global_load_dwordx4 v[62:65], v[62:63], off
.LBB0_345:
	s_setprio 1
	s_waitcnt lgkmcnt(3)
	v_mfma_f32_16x16x32_bf16 v[66:69], v[138:141], v[154:157], v[66:69]
	s_waitcnt lgkmcnt(2)
	v_mfma_f32_16x16x32_bf16 v[70:73], v[138:141], v[158:161], v[70:73]
	s_waitcnt lgkmcnt(1)
	v_mfma_f32_16x16x32_bf16 v[74:77], v[138:141], v[162:165], v[74:77]
	s_waitcnt lgkmcnt(0)
	v_mfma_f32_16x16x32_bf16 v[78:81], v[138:141], v[166:169], v[78:81]
	v_mfma_f32_16x16x32_bf16 v[82:85], v[142:145], v[154:157], v[82:85]
	v_mfma_f32_16x16x32_bf16 v[86:89], v[142:145], v[158:161], v[86:89]
	v_mfma_f32_16x16x32_bf16 v[90:93], v[142:145], v[162:165], v[90:93]
	v_mfma_f32_16x16x32_bf16 v[94:97], v[142:145], v[166:169], v[94:97]
	v_mfma_f32_16x16x32_bf16 v[138:141], v[146:149], v[154:157], v[98:101]
	v_mfma_f32_16x16x32_bf16 v[142:145], v[146:149], v[158:161], v[102:105]
	v_mfma_f32_16x16x32_bf16 v[190:193], v[146:149], v[162:165], v[106:109]
	v_mfma_f32_16x16x32_bf16 v[146:149], v[146:149], v[166:169], v[110:113]
	v_mfma_f32_16x16x32_bf16 v[154:157], v[150:153], v[154:157], v[114:117]
	v_mfma_f32_16x16x32_bf16 v[158:161], v[150:153], v[158:161], v[118:121]
	v_mfma_f32_16x16x32_bf16 v[162:165], v[150:153], v[162:165], v[122:125]
	v_mfma_f32_16x16x32_bf16 v[150:153], v[150:153], v[166:169], v[126:129]
	s_setprio 0
	ds_read_b128 v[98:101], v136 offset:32768
	ds_read_b128 v[166:169], v136 offset:34816
	ds_read_b128 v[194:197], v136 offset:36864
	ds_read_b128 v[198:201], v136 offset:38912
	ds_read_b128 v[202:205], v137 offset:49152
	ds_read_b128 v[206:209], v137 offset:51200
	ds_read_b128 v[210:213], v137 offset:53248
	ds_read_b128 v[234:237], v137 offset:55296
	s_setprio 1
	s_waitcnt lgkmcnt(3)
	v_mfma_f32_16x16x32_bf16 v[126:129], v[98:101], v[202:205], v[66:69]
	s_waitcnt lgkmcnt(2)
	v_mfma_f32_16x16x32_bf16 v[122:125], v[98:101], v[206:209], v[70:73]
	s_waitcnt lgkmcnt(1)
	v_mfma_f32_16x16x32_bf16 v[114:117], v[98:101], v[210:213], v[74:77]
	s_waitcnt lgkmcnt(0)
	v_mfma_f32_16x16x32_bf16 v[106:109], v[98:101], v[234:237], v[78:81]
	v_mfma_f32_16x16x32_bf16 v[118:121], v[166:169], v[202:205], v[82:85]
	v_mfma_f32_16x16x32_bf16 v[110:113], v[166:169], v[206:209], v[86:89]
	v_mfma_f32_16x16x32_bf16 v[102:105], v[166:169], v[210:213], v[90:93]
	v_mfma_f32_16x16x32_bf16 v[98:101], v[166:169], v[234:237], v[94:97]
	v_mfma_f32_16x16x32_bf16 v[94:97], v[194:197], v[202:205], v[138:141]
	v_mfma_f32_16x16x32_bf16 v[90:93], v[194:197], v[206:209], v[142:145]
	v_mfma_f32_16x16x32_bf16 v[82:85], v[194:197], v[210:213], v[190:193]
	v_mfma_f32_16x16x32_bf16 v[74:77], v[194:197], v[234:237], v[146:149]
	v_mfma_f32_16x16x32_bf16 v[86:89], v[198:201], v[202:205], v[154:157]
	v_mfma_f32_16x16x32_bf16 v[78:81], v[198:201], v[206:209], v[158:161]
	v_mfma_f32_16x16x32_bf16 v[70:73], v[198:201], v[210:213], v[162:165]
	v_mfma_f32_16x16x32_bf16 v[66:69], v[198:201], v[234:237], v[150:153]
	s_setprio 0
	s_andn2_b64 vcc, exec, s[36:37]
	s_addk_i32 s11, 0x80
	s_cbranch_vccz .LBB0_347
	s_mov_b32 s90, s0
	s_branch .LBB0_336

.LBB0_699:
	s_cmp_gt_u32 s83, 29
	s_cselect_b64 s[30:31], -1, 0
	s_and_b64 vcc, exec, s[30:31]
	s_waitcnt vmcnt(13)
	ds_write_b128 v133, v[2:5]
	s_waitcnt vmcnt(12)
	ds_write_b128 v133, v[14:17] offset:16384
	ds_write_b128 v133, v[10:13] offset:4096
	s_waitcnt vmcnt(10)
	ds_write_b128 v133, v[26:29] offset:20480
	ds_write_b128 v133, v[18:21] offset:8192
	s_waitcnt vmcnt(9)
	ds_write_b128 v133, v[46:49] offset:24576
	ds_write_b128 v133, v[38:41] offset:12288
	s_waitcnt vmcnt(8)
	ds_write_b128 v133, v[58:61] offset:28672
	s_waitcnt lgkmcnt(0)
	s_barrier
	ds_read_b128 v[148:151], v135
	ds_read_b128 v[152:155], v135 offset:2048
	ds_read_b128 v[156:159], v135 offset:4096
	ds_read_b128 v[160:163], v135 offset:6144
	ds_read_b128 v[164:167], v144 offset:16384
	ds_read_b128 v[168:171], v144 offset:18432
	ds_read_b128 v[180:183], v144 offset:20480
	ds_read_b128 v[184:187], v144 offset:22528
	s_cbranch_vccz .LBB0_701
	s_mov_b64 s[36:37], 0
	s_mov_b64 s[34:35], s[24:25]
	s_branch .LBB0_702

.LBB0_706:
	s_setprio 1
	s_waitcnt lgkmcnt(3)
	v_mfma_f32_16x16x32_bf16 v[126:129], v[148:151], v[164:167], v[126:129]
	s_waitcnt lgkmcnt(2)
	v_mfma_f32_16x16x32_bf16 v[118:121], v[148:151], v[168:171], v[118:121]
	s_waitcnt lgkmcnt(1)
	v_mfma_f32_16x16x32_bf16 v[102:105], v[148:151], v[180:183], v[102:105]
	s_waitcnt lgkmcnt(0)
	v_mfma_f32_16x16x32_bf16 v[86:89], v[148:151], v[184:187], v[86:89]
	v_mfma_f32_16x16x32_bf16 v[122:125], v[152:155], v[164:167], v[122:125]
	v_mfma_f32_16x16x32_bf16 v[110:113], v[152:155], v[168:171], v[110:113]
	v_mfma_f32_16x16x32_bf16 v[94:97], v[152:155], v[180:183], v[94:97]
	v_mfma_f32_16x16x32_bf16 v[114:117], v[156:159], v[164:167], v[114:117]
	v_mfma_f32_16x16x32_bf16 v[148:151], v[152:155], v[184:187], v[78:81]
	v_mfma_f32_16x16x32_bf16 v[152:155], v[156:159], v[168:171], v[98:101]
	v_mfma_f32_16x16x32_bf16 v[188:191], v[156:159], v[180:183], v[82:85]
	v_mfma_f32_16x16x32_bf16 v[156:159], v[156:159], v[184:187], v[70:73]
	v_mfma_f32_16x16x32_bf16 v[164:167], v[160:163], v[164:167], v[106:109]
	v_mfma_f32_16x16x32_bf16 v[168:171], v[160:163], v[168:171], v[90:93]
	v_mfma_f32_16x16x32_bf16 v[180:183], v[160:163], v[180:183], v[74:77]
	v_mfma_f32_16x16x32_bf16 v[160:163], v[160:163], v[184:187], v[66:69]
	s_setprio 0
	ds_read_b128 v[78:81], v145
	ds_read_b128 v[98:101], v145 offset:2048
	ds_read_b128 v[184:187], v145 offset:4096
	ds_read_b128 v[192:195], v145 offset:6144
	ds_read_b128 v[196:199], v146 offset:16384
	ds_read_b128 v[200:203], v146 offset:18432
	ds_read_b128 v[204:207], v146 offset:20480
	ds_read_b128 v[208:211], v146 offset:22528
	s_setprio 1
	s_waitcnt lgkmcnt(3)
	v_mfma_f32_16x16x32_bf16 v[66:69], v[78:81], v[196:199], v[126:129]
	s_waitcnt lgkmcnt(2)
	v_mfma_f32_16x16x32_bf16 v[70:73], v[78:81], v[200:203], v[118:121]
	s_waitcnt lgkmcnt(1)
	v_mfma_f32_16x16x32_bf16 v[74:77], v[78:81], v[204:207], v[102:105]
	s_waitcnt lgkmcnt(0)
	v_mfma_f32_16x16x32_bf16 v[78:81], v[78:81], v[208:211], v[86:89]
	v_mfma_f32_16x16x32_bf16 v[82:85], v[98:101], v[196:199], v[122:125]
	v_mfma_f32_16x16x32_bf16 v[86:89], v[98:101], v[200:203], v[110:113]
	v_mfma_f32_16x16x32_bf16 v[90:93], v[98:101], v[204:207], v[94:97]
	v_mfma_f32_16x16x32_bf16 v[94:97], v[98:101], v[208:211], v[148:151]
	v_mfma_f32_16x16x32_bf16 v[98:101], v[184:187], v[196:199], v[114:117]
	v_mfma_f32_16x16x32_bf16 v[102:105], v[184:187], v[200:203], v[152:155]
	v_mfma_f32_16x16x32_bf16 v[106:109], v[184:187], v[204:207], v[188:191]
	v_mfma_f32_16x16x32_bf16 v[110:113], v[184:187], v[208:211], v[156:159]
	v_mfma_f32_16x16x32_bf16 v[114:117], v[192:195], v[196:199], v[164:167]
	v_mfma_f32_16x16x32_bf16 v[118:121], v[192:195], v[200:203], v[168:171]
	v_mfma_f32_16x16x32_bf16 v[122:125], v[192:195], v[204:207], v[180:183]
	v_mfma_f32_16x16x32_bf16 v[126:129], v[192:195], v[208:211], v[160:163]
	s_setprio 0
	s_cmp_lt_u32 s83, 29
	s_cselect_b64 s[34:35], -1, 0
	s_or_b64 s[36:37], s[24:25], s[34:35]
	s_andn2_b64 vcc, exec, s[36:37]
	s_cbranch_vccnz .Lgout_sh_tail
	s_waitcnt vmcnt(15)
	ds_write_b128 v133, v[6:9] offset:32768
	s_waitcnt vmcnt(11)
	ds_write_b128 v133, v[22:25] offset:49152
	ds_write_b128 v133, v[30:33] offset:36864
	s_waitcnt vmcnt(10)
	ds_write_b128 v133, v[42:45] offset:53248
	ds_write_b128 v133, v[34:37] offset:40960
	s_waitcnt vmcnt(9)
	ds_write_b128 v133, v[54:57] offset:57344
	ds_write_b128 v133, v[50:53] offset:45056
	s_waitcnt vmcnt(8)
	ds_write_b128 v133, v[62:65] offset:61440
	s_branch .Lgout_sh_join

.Lgout_sh_join:
	s_waitcnt lgkmcnt(0)
	s_barrier
	ds_read_b128 v[148:151], v135 offset:32768
	ds_read_b128 v[152:155], v135 offset:34816
	ds_read_b128 v[156:159], v135 offset:36864
	ds_read_b128 v[160:163], v135 offset:38912
	ds_read_b128 v[164:167], v144 offset:49152
	ds_read_b128 v[168:171], v144 offset:51200
	ds_read_b128 v[180:183], v144 offset:53248
	ds_read_b128 v[184:187], v144 offset:55296
	s_cbranch_vccnz .LBB0_708
	s_and_b64 s[34:35], s[34:35], exec
	s_cselect_b32 s35, s19, s81
	s_cselect_b32 s34, s18, s80
	v_lshl_add_u64 v[6:7], s[34:35], 0, v[140:141]
	s_cselect_b32 s35, s15, s79
	s_cselect_b32 s34, s14, s11
	v_lshl_add_u64 v[8:9], s[34:35], 0, v[140:141]
	s_movk_i32 s34, 0xf8c0
	s_cselect_b32 s34, 0xc0, s34
	s_add_i32 s34, s34, s82
	s_add_i32 s42, s34, 0x780
	v_lshl_add_u64 v[8:9], v[8:9], 0, v[0:1]
	s_lshl_b64 s[34:35], s[42:43], 1
	v_lshl_add_u64 v[22:23], v[8:9], 0, s[34:35]
	v_add_co_u32_e32 v24, vcc, s60, v22
	v_lshl_add_u64 v[6:7], v[6:7], 0, v[0:1]
	s_nop 0
	v_addc_co_u32_e32 v25, vcc, 0, v23, vcc
	v_add_co_u32_e32 v34, vcc, 0x40000, v22
	v_lshl_add_u64 v[62:63], v[6:7], 0, s[34:35]
	s_nop 0
	v_addc_co_u32_e32 v35, vcc, 0, v23, vcc
	global_load_dwordx4 v[6:9], v[22:23], off
	v_add_co_u32_e32 v22, vcc, 0x60000, v22
	global_load_dwordx4 v[30:33], v[24:25], off
	s_nop 0
	global_load_dwordx4 v[34:37], v[34:35], off
	v_addc_co_u32_e32 v23, vcc, 0, v23, vcc
	v_add_co_u32_e32 v42, vcc, 0x20000, v62
	global_load_dwordx4 v[50:53], v[22:23], off
	s_nop 0
	global_load_dwordx4 v[22:25], v[62:63], off
	v_addc_co_u32_e32 v43, vcc, 0, v63, vcc
	v_add_co_u32_e32 v54, vcc, 0x40000, v62
	s_nop 1
	v_addc_co_u32_e32 v55, vcc, 0, v63, vcc
	v_add_co_u32_e32 v62, vcc, 0x60000, v62
	global_load_dwordx4 v[42:45], v[42:43], off
	s_nop 0
	global_load_dwordx4 v[54:57], v[54:55], off
	v_addc_co_u32_e32 v63, vcc, 0, v63, vcc
	global_load_dwordx4 v[62:65], v[62:63], off
.LBB0_708:
	s_setprio 1
	s_waitcnt lgkmcnt(3)
	v_mfma_f32_16x16x32_bf16 v[66:69], v[148:151], v[164:167], v[66:69]
	s_waitcnt lgkmcnt(2)
	v_mfma_f32_16x16x32_bf16 v[70:73], v[148:151], v[168:171], v[70:73]
	s_waitcnt lgkmcnt(1)
	v_mfma_f32_16x16x32_bf16 v[74:77], v[148:151], v[180:183], v[74:77]
	s_waitcnt lgkmcnt(0)
	v_mfma_f32_16x16x32_bf16 v[78:81], v[148:151], v[184:187], v[78:81]
	v_mfma_f32_16x16x32_bf16 v[82:85], v[152:155], v[164:167], v[82:85]
	v_mfma_f32_16x16x32_bf16 v[90:93], v[152:155], v[180:183], v[90:93]
	v_mfma_f32_16x16x32_bf16 v[98:101], v[156:159], v[164:167], v[98:101]
	v_mfma_f32_16x16x32_bf16 v[106:109], v[156:159], v[180:183], v[106:109]
	v_mfma_f32_16x16x32_bf16 v[148:151], v[152:155], v[168:171], v[86:89]
	v_mfma_f32_16x16x32_bf16 v[152:155], v[152:155], v[184:187], v[94:97]
	v_mfma_f32_16x16x32_bf16 v[188:191], v[156:159], v[168:171], v[102:105]
	v_mfma_f32_16x16x32_bf16 v[156:159], v[156:159], v[184:187], v[110:113]
	v_mfma_f32_16x16x32_bf16 v[164:167], v[160:163], v[164:167], v[114:117]
	v_mfma_f32_16x16x32_bf16 v[168:171], v[160:163], v[168:171], v[118:121]
	v_mfma_f32_16x16x32_bf16 v[180:183], v[160:163], v[180:183], v[122:125]
	v_mfma_f32_16x16x32_bf16 v[160:163], v[160:163], v[184:187], v[126:129]
	s_setprio 0
	ds_read_b128 v[86:89], v145 offset:32768
	ds_read_b128 v[114:117], v145 offset:34816
	ds_read_b128 v[184:187], v145 offset:36864
	ds_read_b128 v[192:195], v145 offset:38912
	ds_read_b128 v[196:199], v146 offset:49152
	ds_read_b128 v[200:203], v146 offset:51200
	ds_read_b128 v[204:207], v146 offset:53248
	ds_read_b128 v[208:211], v146 offset:55296
	s_setprio 1
	s_waitcnt lgkmcnt(3)
	v_mfma_f32_16x16x32_bf16 v[126:129], v[86:89], v[196:199], v[66:69]
	s_waitcnt lgkmcnt(2)
	v_mfma_f32_16x16x32_bf16 v[118:121], v[86:89], v[200:203], v[70:73]
	s_waitcnt lgkmcnt(1)
	v_mfma_f32_16x16x32_bf16 v[102:105], v[86:89], v[204:207], v[74:77]
	s_waitcnt lgkmcnt(0)
	v_mfma_f32_16x16x32_bf16 v[86:89], v[86:89], v[208:211], v[78:81]
	v_mfma_f32_16x16x32_bf16 v[122:125], v[114:117], v[196:199], v[82:85]
	v_mfma_f32_16x16x32_bf16 v[110:113], v[114:117], v[200:203], v[148:151]
	v_mfma_f32_16x16x32_bf16 v[94:97], v[114:117], v[204:207], v[90:93]
	v_mfma_f32_16x16x32_bf16 v[78:81], v[114:117], v[208:211], v[152:155]
	v_mfma_f32_16x16x32_bf16 v[114:117], v[184:187], v[196:199], v[98:101]
	v_mfma_f32_16x16x32_bf16 v[98:101], v[184:187], v[200:203], v[188:191]
	v_mfma_f32_16x16x32_bf16 v[82:85], v[184:187], v[204:207], v[106:109]
	v_mfma_f32_16x16x32_bf16 v[70:73], v[184:187], v[208:211], v[156:159]
	v_mfma_f32_16x16x32_bf16 v[106:109], v[192:195], v[196:199], v[164:167]
	v_mfma_f32_16x16x32_bf16 v[90:93], v[192:195], v[200:203], v[168:171]
	v_mfma_f32_16x16x32_bf16 v[74:77], v[192:195], v[204:207], v[180:183]
	v_mfma_f32_16x16x32_bf16 v[66:69], v[192:195], v[208:211], v[160:163]
	s_setprio 0
	s_andn2_b64 vcc, exec, s[30:31]
	s_addk_i32 s82, 0x80
	s_cbranch_vccz .LBB0_666
	s_mov_b32 s83, s0
	s_branch .LBB0_699
